# replace grid barrier between out-proj(l0) and in-proj(l1) by 4-workgroup panel-group barrier
# speedup vs baseline: 1.0150x; 1.0010x over previous
; #define LAS __attribute__((address_space(3)))
; __device__ __forceinline__ unsigned xb_add(unsigned* p, unsigned v) { return __hip_atomic_fetch_add(p, v, __ATOMIC_RELAXED, __HIP_MEMORY_SCOPE_AGENT); }
; __device__ __forceinline__ unsigned xb_xcc_id() { return (unsigned)__builtin_amdgcn_s_getreg((3 << 11) | 20) & 0xFu; }
; __device__ __forceinline__ XcdBarrier xcd_barrier_post(unsigned* bar, volatile LAS unsigned* st) {
;     XcdBarrier b; b.bar = bar; b.x = xb_xcc_id(); b.st = st;
;     if (threadIdx.x == 0) (void)xb_add(&bar[XB_XCNT(b.x)], 1u);
;     return b;
; }
; __global__ void __launch_bounds__(512) hymba_fwd(Args a) {
;     ...
;     volatile LAS unsigned* xst = (volatile LAS unsigned*)(lds + LDS_BYTES - 16);
;     if (threadIdx.x < 2) xst[threadIdx.x] = 0u;
;     __syncthreads();
;     XcdBarrier xbar; xbar.bar = (unsigned*)(a.ws + WS_BAR); xbar.x = 0; xbar.st = xst;
;     if (hi - lo > 1) xbar = xcd_barrier_post((unsigned*)(a.ws + WS_BAR), xst);
_Z9hymba_fwd4Args:
	s_load_dwordx16 s[64:79], s[0:1], 0x40
	s_load_dwordx2 s[4:5], s[0:1], 0x80
	s_load_dword s3, s[0:1], 0x90
	v_and_b32_e32 v178, 0x3ff, v0
	v_cmp_gt_u32_e32 vcc, 2, v178
	s_waitcnt lgkmcnt(0)
	v_writelane_b32 v246, s4, 0
	s_nop 1
	v_writelane_b32 v246, s5, 1
	s_add_u32 s4, s0, 0x90
	s_addc_u32 s5, s1, 0
	v_writelane_b32 v246, s4, 2
	s_nop 1
	v_writelane_b32 v246, s5, 3
	s_and_saveexec_b64 s[4:5], vcc
	v_lshl_add_u32 v1, v178, 2, 0
	v_add_u32_e32 v1, 0x23ff0, v1
	v_mov_b32_e32 v2, 0
	ds_write_b32 v1, v2
	s_or_b64 exec, exec, s[4:5]
	s_load_dwordx2 s[4:5], s[0:1], 0x80
	s_load_dwordx16 s[80:95], s[0:1], 0x0
	s_add_u32 s12, s78, 0xfc00000
	s_addc_u32 s13, s79, 0
	s_mov_b32 s48, 0
	s_waitcnt lgkmcnt(0)
	s_sub_i32 s4, s5, s4
	s_cmp_lt_i32 s4, 2
	v_cmp_eq_u32_e32 vcc, 0, v178
	s_barrier
	s_cbranch_scc1 .LBB0_7
	s_getreg_b32 s4, hwreg(HW_REG_XCC_ID, 0, 4)
	s_and_b32 s48, s4, 15
	s_and_saveexec_b64 s[4:5], vcc
	s_cbranch_execz .LBB0_6
	s_mov_b64 s[6:7], exec
	v_mbcnt_lo_u32_b32 v1, s6, 0
	v_mbcnt_hi_u32_b32 v1, s7, v1
	v_cmp_eq_u32_e32 vcc, 0, v1
	s_and_b64 s[8:9], exec, vcc
	s_mov_b64 exec, s[8:9]
	s_cbranch_execz .LBB0_6
	s_lshl_b32 s8, s48, 8
	s_bcnt1_i32_b64 s6, s[6:7]
	v_mov_b32_e32 v1, s8
	v_mov_b32_e32 v2, s6
	global_atomic_add v1, v2, s[12:13] offset:1024
	s_and_b32 s98, s2, 7
	s_lshl_b32 s98, s98, 3
	s_bfe_u32 s99, s2, 0x30003
	s_or_b32 s98, s98, s99
	s_lshl_b32 s98, s98, 2
	s_lshl_b32 s99, 1, s48
	v_mov_b32_e32 v3, s98
	v_mov_b32_e32 v4, s99
	global_atomic_or v3, v4, s[12:13] offset:256

; #define SEAM(k) do { if (IN(k) && IN((k) + 1)) { if (a.pad == 0x5eed) cg::this_grid().sync(); xcd_barrier(xbar); } } while (0)
; __global__ void __launch_bounds__(512) hymba_fwd(Args a) {
;     ...
;         if (l == 0) SEAM(base + 4);
.LBB0_809:
.LBB0_810:
	v_readlane_b32 s4, v244, 46
	v_readlane_b32 s8, v244, 2
	v_readlane_b32 s5, v244, 47
	v_readlane_b32 s9, v244, 3
	s_and_b64 s[4:5], s[4:5], s[48:49]
	s_and_b64 s[8:9], s[50:51], s[8:9]
	s_and_b64 s[4:5], s[4:5], s[8:9]
	s_andn2_b64 vcc, exec, s[4:5]
	s_cbranch_vccnz .LBB0_155
	s_cmp_eq_u32 s3, 0x100
	s_cbranch_scc1 .Lgb4
	s_and_b64 vcc, exec, s[96:97]
	s_cbranch_vccnz .LBB0_823
	s_barrier
	s_mov_b64 s[14:15], exec
	v_readlane_b32 s4, v244, 4
	v_readlane_b32 s5, v244, 5
	s_and_b64 s[4:5], s[14:15], s[4:5]
	s_mov_b64 exec, s[4:5]
	s_cbranch_execz .LBB0_822
	v_readlane_b32 s4, v246, 2
	v_readlane_b32 s5, v246, 3
	buffer_wbl2 sc1
	s_waitcnt vmcnt(0)
	s_load_dwordx2 s[16:17], s[4:5], 0x58
	s_mov_b64 s[18:19], exec
	v_mbcnt_lo_u32_b32 v1, s18, 0
	v_mbcnt_hi_u32_b32 v1, s19, v1
	v_cmp_eq_u32_e32 vcc, 0, v1
	s_waitcnt lgkmcnt(0)
	global_load_dword v0, v145, s[16:17] offset:40
	s_and_saveexec_b64 s[40:41], vcc
	s_cbranch_execz .LBB0_815
	s_bcnt1_i32_b64 s4, s[18:19]
	v_mov_b32_e32 v2, s4
	global_atomic_add v2, v145, v2, s[16:17] offset:32 sc0

; __device__ __forceinline__ unsigned xb_ld(unsigned* p)              { return __hip_atomic_load(p, __ATOMIC_RELAXED, __HIP_MEMORY_SCOPE_AGENT); }
; __device__ __forceinline__ unsigned xb_add(unsigned* p, unsigned v) { return __hip_atomic_fetch_add(p, v, __ATOMIC_RELAXED, __HIP_MEMORY_SCOPE_AGENT); }
; #define XB_SPIN(cond, bar) do { unsigned _sp = 0; while (cond) { __builtin_amdgcn_s_sleep(1); \
;     if ((++_sp & 255u) == 0u) { if (xb_ld(&(bar)[XB_TMO])) break; if (_sp > XB_SPIN_CAP) { atomicAdd(&(bar)[XB_TMO], 1u); break; } } } } while (0)
; __device__ __forceinline__ void xcd_barrier(const XcdBarrier& b) {
;     asm volatile("s_waitcnt vmcnt(0)" ::: "memory");
;     __syncthreads();
;     if (threadIdx.x == 0) {
;         unsigned* bar = b.bar;
;         __builtin_amdgcn_s_waitcnt(0);
;         unsigned nloc = b.st[0], nx = b.st[1];
;         if (nloc == 0u) { xcd_barrier_complete(bar, b.x, nloc, nx); b.st[0] = nloc; b.st[1] = nx; }
;         const unsigned old = xb_add(&bar[XB_XSUB(b.x)], 1u);
;         const unsigned gen = old / nloc;
;         if (old + 1u == (gen + 1u) * nloc) {
;             __builtin_amdgcn_fence(__ATOMIC_RELEASE, "agent");
;             asm volatile("s_waitcnt vmcnt(0)" ::: "memory");
;             const unsigned og = xb_add(&bar[XB_TOP], 1u);
;             const unsigned tg = og / nx;
;             if (og + 1u == (tg + 1u) * nx) xb_add(&bar[XB_TOPGEN], 1u);
;             else XB_SPIN(xb_ld(&bar[XB_TOPGEN]) == tg, bar);
;             __builtin_amdgcn_fence(__ATOMIC_ACQUIRE, "agent");
;             xb_add(&bar[XB_XGEN(b.x)], 1u);
;             asm volatile("s_waitcnt vmcnt(0)" ::: "memory");
;         } else {
;             XB_SPIN(xb_ld(&bar[XB_XGEN(b.x)]) == gen, bar);
;             __builtin_amdgcn_fence(__ATOMIC_ACQUIRE, "agent");
;             asm volatile("s_waitcnt vmcnt(0)" ::: "memory");
;         }
;     }
;     __syncthreads();
; }
.Lgb4:
	s_add_u32 s8, s78, 0xfc00000
	s_addc_u32 s9, s79, 0
	s_and_b32 s4, s2, 7
	s_lshl_b32 s4, s4, 3
	s_bfe_u32 s5, s2, 0x30003
	s_or_b32 s4, s4, s5
	s_lshl_b32 s4, s4, 2
	v_cmp_eq_u32_e32 vcc, 0, v178
	s_and_saveexec_b64 s[14:15], vcc
	s_cbranch_execz .Lgb4_join
	v_mov_b32_e32 v0, s4
	v_mov_b32_e32 v2, 1
	global_load_dword v1, v0, s[8:9] offset:256 sc1
	s_waitcnt vmcnt(0)
	v_readfirstlane_b32 s5, v1
	s_bcnt1_i32_b32 s5, s5
	s_cmp_eq_u32 s5, 1
	s_cbranch_scc1 .Lgb4_fast
	buffer_wbl2 sc1
	s_waitcnt vmcnt(0)
.Lgb4_fast:
	global_atomic_add v0, v2, s[8:9]
	s_mov_b32 s5, 0
.Lgb4_spin:
	global_load_dword v1, v0, s[8:9] sc1
	s_waitcnt vmcnt(0)
	v_readfirstlane_b32 s10, v1
	s_cmp_ge_u32 s10, 4
	s_cbranch_scc1 .Lgb4_done
	s_sleep 1
	s_add_i32 s5, s5, 1
	s_cmp_lt_u32 s5, 0x40000
	s_cbranch_scc1 .Lgb4_spin
.Lgb4_done:
	buffer_inv sc1
	s_waitcnt vmcnt(0)
.Lgb4_join:
	s_or_b64 exec, exec, s[14:15]
	s_barrier
	s_branch .LBB0_155

; __global__ void __launch_bounds__(512) hymba_fwd(Args a) {
	.amdhsa_kernel _Z9hymba_fwd4Args
		.amdhsa_group_segment_fixed_size 0
		.amdhsa_private_segment_fixed_size 0
		.amdhsa_kernarg_size 400
		.amdhsa_user_sgpr_count 2
		.amdhsa_user_sgpr_dispatch_ptr 0
		.amdhsa_user_sgpr_queue_ptr 0
		.amdhsa_user_sgpr_kernarg_segment_ptr 1
		.amdhsa_user_sgpr_dispatch_id 0
		.amdhsa_user_sgpr_kernarg_preload_length 0
		.amdhsa_user_sgpr_kernarg_preload_offset 0
		.amdhsa_user_sgpr_private_segment_size 0
		.amdhsa_uses_dynamic_stack 0
		.amdhsa_enable_private_segment 0
		.amdhsa_system_sgpr_workgroup_id_x 1
		.amdhsa_system_sgpr_workgroup_id_y 0
		.amdhsa_system_sgpr_workgroup_id_z 0
		.amdhsa_system_sgpr_workgroup_info 0
		.amdhsa_system_vgpr_workitem_id 2
		.amdhsa_next_free_vgpr 248
		.amdhsa_next_free_sgpr 100
		.amdhsa_accum_offset 248
		.amdhsa_reserve_vcc 1
		.amdhsa_float_round_mode_32 0
		.amdhsa_float_round_mode_16_64 0
		.amdhsa_float_denorm_mode_32 3
		.amdhsa_float_denorm_mode_16_64 3
		.amdhsa_dx10_clamp 1
		.amdhsa_ieee_mode 1
		.amdhsa_fp16_overflow 0
		.amdhsa_tg_split 0
		.amdhsa_exception_fp_ieee_invalid_op 0
		.amdhsa_exception_fp_denorm_src 0
		.amdhsa_exception_fp_ieee_div_zero 0
		.amdhsa_exception_fp_ieee_overflow 0
		.amdhsa_exception_fp_ieee_underflow 0
		.amdhsa_exception_fp_ieee_inexact 0
		.amdhsa_exception_int_div_zero 0
	.end_amdhsa_kernel

; __global__ void __launch_bounds__(512) hymba_fwd(Args a) {
amdhsa.kernels:
  - .agpr_count:     0
    .args:
      - .offset:         0
        .size:           144
        .value_kind:     by_value
      - .offset:         144
        .size:           4
        .value_kind:     hidden_block_count_x
      - .offset:         148
        .size:           4
        .value_kind:     hidden_block_count_y
      - .offset:         152
        .size:           4
        .value_kind:     hidden_block_count_z
      - .offset:         156
        .size:           2
        .value_kind:     hidden_group_size_x
      - .offset:         158
        .size:           2
        .value_kind:     hidden_group_size_y
      - .offset:         160
        .size:           2
        .value_kind:     hidden_group_size_z
      - .offset:         162
        .size:           2
        .value_kind:     hidden_remainder_x
      - .offset:         164
        .size:           2
        .value_kind:     hidden_remainder_y
      - .offset:         166
        .size:           2
        .value_kind:     hidden_remainder_z
      - .offset:         184
        .size:           8
        .value_kind:     hidden_global_offset_x
      - .offset:         192
        .size:           8
        .value_kind:     hidden_global_offset_y
      - .offset:         200
        .size:           8
        .value_kind:     hidden_global_offset_z
      - .offset:         208
        .size:           2
        .value_kind:     hidden_grid_dims
      - .offset:         232
        .size:           8
        .value_kind:     hidden_multigrid_sync_arg
      - .offset:         264
        .size:           4
        .value_kind:     hidden_dynamic_lds_size
    .group_segment_fixed_size: 0
    .kernarg_segment_align: 8
    .kernarg_segment_size: 400
    .language:       OpenCL C
    .language_version:
      - 2
      - 0
    .max_flat_workgroup_size: 512
    .name:           _Z9hymba_fwd4Args
    .private_segment_fixed_size: 0
    .sgpr_count:     106
    .sgpr_spill_count: 193
    .symbol:         _Z9hymba_fwd4Args.kd
    .uniform_work_group_size: 1
    .uses_dynamic_stack: false
    .vgpr_count:     248
    .vgpr_spill_count: 0
    .wavefront_size: 64
